# v28 plus accumulator zeroing in all seven GEMM tile headers done with 64 v_mov_b64 instead of 128 v_mov_b32
# baseline (speedup 1.0000x reference)
;     __device__ bool next(int i, Unit& u) const { Unit b; if (!so.next(i / 3, b)) return false; const int br = i % 3; u.pm = br * 64 + b.pm; u.pn = br * 8 + b.pn; return true; }
; template <class Epi, class Sched>
; __device__ __forceinline__ void gemm_phase(const int tid, LAS unsigned char* lds, const Gemm g, const Sched& S, const Epi& E) {
;     ...
;     for (;;) {
;         const bool has_next = S.next(ui + 1, nxt);
;         const char* nA = has_next ? (const char*)g.A + (size_t)nxt.pm * tstepA : cA; const char* nB = has_next ? (const char*)g.Bt + (size_t)nxt.pn * tstepB : cB;
;         for (int t = 0; t < nt; t += 2) {
;     ...
;         for (int a = 0; a < 2; ++a)
; #pragma unroll
;             for (int b = 0; b < 2; ++b)
; #pragma unroll
;                 for (int m = 0; m < 4; ++m)
; #pragma unroll
;                     for (int n = 0; n < 2; ++n) acc[a][b][m][n] = (f32x4){0.f, 0.f, 0.f, 0.f};
;         cur = nxt; cA = nA; cB = nB; ++ui;
.LBB0_134:
	s_ashr_i32 s19, s18, 31
	s_lshl_b64 s[20:21], s[18:19], 20
	s_add_u32 s20, s34, s20
	s_addc_u32 s21, s35, s21
	s_and_b64 s[22:23], s[4:5], exec
	s_cselect_b32 s13, s21, s25
	s_cselect_b32 s19, s20, s24
	s_ashr_i32 s17, s16, 31
	s_lshl_b64 s[22:23], s[16:17], 20
	s_add_u32 s22, s52, s22
	s_addc_u32 s23, s53, s23
	s_and_b64 s[26:27], s[4:5], exec
	s_cselect_b32 s17, s23, s7
	s_cselect_b32 s63, s22, s6
	s_add_u32 s64, s6, 0x10000
	s_addc_u32 s65, s7, 0
	s_add_u32 s6, s24, 0xc000
	s_addc_u32 s7, s25, 0
	s_mov_b32 s66, -2
	v_mov_b64_e32 v[2:3], 0
	v_mov_b64_e32 v[4:5], 0
	v_mov_b64_e32 v[6:7], 0
	v_mov_b64_e32 v[8:9], 0
	v_mov_b64_e32 v[18:19], 0
	v_mov_b64_e32 v[20:21], 0
	v_mov_b64_e32 v[22:23], 0
	v_mov_b64_e32 v[24:25], 0
	v_mov_b64_e32 v[34:35], 0
	v_mov_b64_e32 v[36:37], 0
	v_mov_b64_e32 v[38:39], 0
	v_mov_b64_e32 v[40:41], 0
	v_mov_b64_e32 v[50:51], 0
	v_mov_b64_e32 v[52:53], 0
	v_mov_b64_e32 v[54:55], 0
	v_mov_b64_e32 v[56:57], 0
	v_mov_b64_e32 v[10:11], 0
	v_mov_b64_e32 v[12:13], 0
	v_mov_b64_e32 v[14:15], 0
	v_mov_b64_e32 v[16:17], 0
	v_mov_b64_e32 v[26:27], 0
	v_mov_b64_e32 v[28:29], 0
	v_mov_b64_e32 v[30:31], 0
	v_mov_b64_e32 v[32:33], 0
	v_mov_b64_e32 v[42:43], 0
	v_mov_b64_e32 v[44:45], 0
	v_mov_b64_e32 v[46:47], 0
	v_mov_b64_e32 v[48:49], 0
	v_mov_b64_e32 v[66:67], 0
	v_mov_b64_e32 v[68:69], 0
	v_mov_b64_e32 v[70:71], 0
	v_mov_b64_e32 v[72:73], 0
	v_mov_b64_e32 v[82:83], 0
	v_mov_b64_e32 v[84:85], 0
	v_mov_b64_e32 v[86:87], 0
	v_mov_b64_e32 v[88:89], 0
	v_mov_b64_e32 v[98:99], 0
	v_mov_b64_e32 v[100:101], 0
	v_mov_b64_e32 v[102:103], 0
	v_mov_b64_e32 v[104:105], 0
	v_mov_b64_e32 v[114:115], 0
	v_mov_b64_e32 v[116:117], 0
	v_mov_b64_e32 v[118:119], 0
	v_mov_b64_e32 v[120:121], 0
	v_mov_b64_e32 v[130:131], 0
	v_mov_b64_e32 v[132:133], 0
	v_mov_b64_e32 v[134:135], 0
	v_mov_b64_e32 v[136:137], 0
	v_mov_b64_e32 v[90:91], 0
	v_mov_b64_e32 v[92:93], 0
	v_mov_b64_e32 v[94:95], 0
	v_mov_b64_e32 v[96:97], 0
	v_mov_b64_e32 v[106:107], 0
	v_mov_b64_e32 v[108:109], 0
	v_mov_b64_e32 v[110:111], 0
	v_mov_b64_e32 v[112:113], 0
	v_mov_b64_e32 v[122:123], 0
	v_mov_b64_e32 v[124:125], 0
	v_mov_b64_e32 v[126:127], 0
	v_mov_b64_e32 v[128:129], 0
	v_mov_b64_e32 v[138:139], 0
	v_mov_b64_e32 v[140:141], 0
	v_mov_b64_e32 v[142:143], 0
	v_mov_b64_e32 v[144:145], 0

;     __device__ bool next(int i, Unit& u) const { Unit b; if (!so.next(i / 3, b)) return false; const int br = i % 3; u.pm = br * 64 + b.pm; u.pn = br * 8 + b.pn; return true; }
; template <class Epi, class Sched>
; __device__ __forceinline__ void gemm_phase(const int tid, LAS unsigned char* lds, const Gemm g, const Sched& S, const Epi& E) {
;     ...
;     for (;;) {
;         const bool has_next = S.next(ui + 1, nxt);
;         const char* nA = has_next ? (const char*)g.A + (size_t)nxt.pm * tstepA : cA; const char* nB = has_next ? (const char*)g.Bt + (size_t)nxt.pn * tstepB : cB;
;         for (int t = 0; t < nt; t += 2) {
;     ...
;         for (int a = 0; a < 2; ++a)
; #pragma unroll
;             for (int b = 0; b < 2; ++b)
; #pragma unroll
;                 for (int m = 0; m < 4; ++m)
; #pragma unroll
;                     for (int n = 0; n < 2; ++n) acc[a][b][m][n] = (f32x4){0.f, 0.f, 0.f, 0.f};
;         cur = nxt; cA = nA; cB = nB; ++ui;
.LBB0_403:
	s_ashr_i32 s13, s12, 31
	s_lshl_b64 s[16:17], s[12:13], 22
	s_add_u32 s16, s24, s16
	s_addc_u32 s17, s25, s17
	s_and_b64 s[6:7], s[6:7], exec
	s_cselect_b32 s13, s17, s21
	s_cselect_b32 s57, s16, s20
	s_add_u32 s58, s18, 0x10000
	s_addc_u32 s59, s19, 0
	s_add_u32 s6, s20, 0x200080
	s_addc_u32 s7, s21, 0
	s_mov_b32 s60, -2
	v_mov_b64_e32 v[2:3], 0
	v_mov_b64_e32 v[4:5], 0
	v_mov_b64_e32 v[6:7], 0
	v_mov_b64_e32 v[8:9], 0
	v_mov_b64_e32 v[10:11], 0
	v_mov_b64_e32 v[12:13], 0
	v_mov_b64_e32 v[14:15], 0
	v_mov_b64_e32 v[16:17], 0
	v_mov_b64_e32 v[26:27], 0
	v_mov_b64_e32 v[28:29], 0
	v_mov_b64_e32 v[30:31], 0
	v_mov_b64_e32 v[32:33], 0
	v_mov_b64_e32 v[42:43], 0
	v_mov_b64_e32 v[44:45], 0
	v_mov_b64_e32 v[46:47], 0
	v_mov_b64_e32 v[48:49], 0
	v_mov_b64_e32 v[18:19], 0
	v_mov_b64_e32 v[20:21], 0
	v_mov_b64_e32 v[22:23], 0
	v_mov_b64_e32 v[24:25], 0
	v_mov_b64_e32 v[34:35], 0
	v_mov_b64_e32 v[36:37], 0
	v_mov_b64_e32 v[38:39], 0
	v_mov_b64_e32 v[40:41], 0
	v_mov_b64_e32 v[50:51], 0
	v_mov_b64_e32 v[52:53], 0
	v_mov_b64_e32 v[54:55], 0
	v_mov_b64_e32 v[56:57], 0
	v_mov_b64_e32 v[58:59], 0
	v_mov_b64_e32 v[60:61], 0
	v_mov_b64_e32 v[62:63], 0
	v_mov_b64_e32 v[64:65], 0
	v_mov_b64_e32 v[66:67], 0
	v_mov_b64_e32 v[68:69], 0
	v_mov_b64_e32 v[70:71], 0
	v_mov_b64_e32 v[72:73], 0
	v_mov_b64_e32 v[74:75], 0
	v_mov_b64_e32 v[76:77], 0
	v_mov_b64_e32 v[78:79], 0
	v_mov_b64_e32 v[80:81], 0
	v_mov_b64_e32 v[90:91], 0
	v_mov_b64_e32 v[92:93], 0
	v_mov_b64_e32 v[94:95], 0
	v_mov_b64_e32 v[96:97], 0
	v_mov_b64_e32 v[106:107], 0
	v_mov_b64_e32 v[108:109], 0
	v_mov_b64_e32 v[110:111], 0
	v_mov_b64_e32 v[112:113], 0
	v_mov_b64_e32 v[82:83], 0
	v_mov_b64_e32 v[84:85], 0
	v_mov_b64_e32 v[86:87], 0
	v_mov_b64_e32 v[88:89], 0
	v_mov_b64_e32 v[98:99], 0
	v_mov_b64_e32 v[100:101], 0
	v_mov_b64_e32 v[102:103], 0
	v_mov_b64_e32 v[104:105], 0
	v_mov_b64_e32 v[114:115], 0
	v_mov_b64_e32 v[116:117], 0
	v_mov_b64_e32 v[118:119], 0
	v_mov_b64_e32 v[120:121], 0
	v_mov_b64_e32 v[122:123], 0
	v_mov_b64_e32 v[124:125], 0
	v_mov_b64_e32 v[126:127], 0
	v_mov_b64_e32 v[128:129], 0

;     __device__ bool next(int i, Unit& u) const { Unit b; if (!so.next(i / 3, b)) return false; const int br = i % 3; u.pm = br * 64 + b.pm; u.pn = br * 8 + b.pn; return true; }
; template <class Epi, class Sched>
; __device__ __forceinline__ void gemm_phase(const int tid, LAS unsigned char* lds, const Gemm g, const Sched& S, const Epi& E) {
;     ...
;     for (;;) {
;         const bool has_next = S.next(ui + 1, nxt);
;         const char* nA = has_next ? (const char*)g.A + (size_t)nxt.pm * tstepA : cA; const char* nB = has_next ? (const char*)g.Bt + (size_t)nxt.pn * tstepB : cB;
;         for (int t = 0; t < nt; t += 2) {
;     ...
;         for (int a = 0; a < 2; ++a)
; #pragma unroll
;             for (int b = 0; b < 2; ++b)
; #pragma unroll
;                 for (int m = 0; m < 4; ++m)
; #pragma unroll
;                     for (int n = 0; n < 2; ++n) acc[a][b][m][n] = (f32x4){0.f, 0.f, 0.f, 0.f};
;         cur = nxt; cA = nA; cB = nB; ++ui;
.LBB0_427:
	s_ashr_i32 s13, s12, 31
	s_lshl_b64 s[14:15], s[12:13], 22
	s_add_u32 s14, s27, s14
	s_addc_u32 s15, s28, s15
	s_and_b64 s[16:17], s[4:5], exec
	s_cselect_b32 s13, s15, s21
	s_cselect_b32 s58, s14, s20
	s_ashr_i32 s11, s10, 31
	s_lshl_b64 s[16:17], s[10:11], 18
	s_add_u32 s16, s29, s16
	s_addc_u32 s17, s30, s17
	s_and_b64 s[22:23], s[4:5], exec
	s_cselect_b32 s11, s17, s19
	s_cselect_b32 s59, s16, s18
	s_add_u32 s60, s18, 0x10000
	s_addc_u32 s61, s19, 0
	s_add_u32 s18, s20, 0x200080
	s_addc_u32 s19, s21, 0
	s_mov_b32 s62, -2
	v_mov_b64_e32 v[2:3], 0
	v_mov_b64_e32 v[4:5], 0
	v_mov_b64_e32 v[6:7], 0
	v_mov_b64_e32 v[8:9], 0
	v_mov_b64_e32 v[10:11], 0
	v_mov_b64_e32 v[12:13], 0
	v_mov_b64_e32 v[14:15], 0
	v_mov_b64_e32 v[16:17], 0
	v_mov_b64_e32 v[26:27], 0
	v_mov_b64_e32 v[28:29], 0
	v_mov_b64_e32 v[30:31], 0
	v_mov_b64_e32 v[32:33], 0
	v_mov_b64_e32 v[42:43], 0
	v_mov_b64_e32 v[44:45], 0
	v_mov_b64_e32 v[46:47], 0
	v_mov_b64_e32 v[48:49], 0
	v_mov_b64_e32 v[18:19], 0
	v_mov_b64_e32 v[20:21], 0
	v_mov_b64_e32 v[22:23], 0
	v_mov_b64_e32 v[24:25], 0
	v_mov_b64_e32 v[34:35], 0
	v_mov_b64_e32 v[36:37], 0
	v_mov_b64_e32 v[38:39], 0
	v_mov_b64_e32 v[40:41], 0
	v_mov_b64_e32 v[50:51], 0
	v_mov_b64_e32 v[52:53], 0
	v_mov_b64_e32 v[54:55], 0
	v_mov_b64_e32 v[56:57], 0
	v_mov_b64_e32 v[58:59], 0
	v_mov_b64_e32 v[60:61], 0
	v_mov_b64_e32 v[62:63], 0
	v_mov_b64_e32 v[64:65], 0
	v_mov_b64_e32 v[66:67], 0
	v_mov_b64_e32 v[68:69], 0
	v_mov_b64_e32 v[70:71], 0
	v_mov_b64_e32 v[72:73], 0
	v_mov_b64_e32 v[74:75], 0
	v_mov_b64_e32 v[76:77], 0
	v_mov_b64_e32 v[78:79], 0
	v_mov_b64_e32 v[80:81], 0
	v_mov_b64_e32 v[90:91], 0
	v_mov_b64_e32 v[92:93], 0
	v_mov_b64_e32 v[94:95], 0
	v_mov_b64_e32 v[96:97], 0
	v_mov_b64_e32 v[106:107], 0
	v_mov_b64_e32 v[108:109], 0
	v_mov_b64_e32 v[110:111], 0
	v_mov_b64_e32 v[112:113], 0
	v_mov_b64_e32 v[82:83], 0
	v_mov_b64_e32 v[84:85], 0
	v_mov_b64_e32 v[86:87], 0
	v_mov_b64_e32 v[88:89], 0
	v_mov_b64_e32 v[98:99], 0
	v_mov_b64_e32 v[100:101], 0
	v_mov_b64_e32 v[102:103], 0
	v_mov_b64_e32 v[104:105], 0
	v_mov_b64_e32 v[114:115], 0
	v_mov_b64_e32 v[116:117], 0
	v_mov_b64_e32 v[118:119], 0
	v_mov_b64_e32 v[120:121], 0
	v_mov_b64_e32 v[122:123], 0
	v_mov_b64_e32 v[124:125], 0
	v_mov_b64_e32 v[126:127], 0
	v_mov_b64_e32 v[128:129], 0

;     __device__ bool next(int i, Unit& u) const { Unit b; if (!so.next(i / 3, b)) return false; const int br = i % 3; u.pm = br * 64 + b.pm; u.pn = br * 8 + b.pn; return true; }
; template <class Epi, class Sched>
; __device__ __forceinline__ void gemm_phase(const int tid, LAS unsigned char* lds, const Gemm g, const Sched& S, const Epi& E) {
;     ...
;     for (;;) {
;         const bool has_next = S.next(ui + 1, nxt);
;         const char* nA = has_next ? (const char*)g.A + (size_t)nxt.pm * tstepA : cA; const char* nB = has_next ? (const char*)g.Bt + (size_t)nxt.pn * tstepB : cB;
;         for (int t = 0; t < nt; t += 2) {
;     ...
;         for (int a = 0; a < 2; ++a)
; #pragma unroll
;             for (int b = 0; b < 2; ++b)
; #pragma unroll
;                 for (int m = 0; m < 4; ++m)
; #pragma unroll
;                     for (int n = 0; n < 2; ++n) acc[a][b][m][n] = (f32x4){0.f, 0.f, 0.f, 0.f};
;         cur = nxt; cA = nA; cB = nB; ++ui;
.LBB0_886:
	s_ashr_i32 s9, s8, 31
	s_lshl_b64 s[12:13], s[8:9], 19
	s_add_u32 s12, s27, s12
	s_addc_u32 s13, s28, s13
	s_and_b64 s[14:15], s[4:5], exec
	s_cselect_b32 s9, s13, s21
	s_cselect_b32 s61, s12, s20
	s_ashr_i32 s11, s10, 31
	s_lshl_b64 s[14:15], s[10:11], 19
	s_add_u32 s14, s29, s14
	s_addc_u32 s15, s30, s15
	s_and_b64 s[22:23], s[4:5], exec
	s_cselect_b32 s11, s15, s19
	s_cselect_b32 s62, s14, s18
	s_add_u32 s63, s18, 0x10000
	s_addc_u32 s64, s19, 0
	s_add_u32 s18, s20, 0x40080
	s_addc_u32 s19, s21, 0
	s_mov_b32 s65, -2
	v_mov_b64_e32 v[2:3], 0
	v_mov_b64_e32 v[4:5], 0
	v_mov_b64_e32 v[6:7], 0
	v_mov_b64_e32 v[8:9], 0
	v_mov_b64_e32 v[18:19], 0
	v_mov_b64_e32 v[20:21], 0
	v_mov_b64_e32 v[22:23], 0
	v_mov_b64_e32 v[24:25], 0
	v_mov_b64_e32 v[30:31], 0
	v_mov_b64_e32 v[32:33], 0
	v_mov_b64_e32 v[38:39], 0
	v_mov_b64_e32 v[40:41], 0
	v_mov_b64_e32 v[50:51], 0
	v_mov_b64_e32 v[52:53], 0
	v_mov_b64_e32 v[54:55], 0
	v_mov_b64_e32 v[56:57], 0
	v_mov_b64_e32 v[10:11], 0
	v_mov_b64_e32 v[12:13], 0
	v_mov_b64_e32 v[14:15], 0
	v_mov_b64_e32 v[16:17], 0
	v_mov_b64_e32 v[26:27], 0
	v_mov_b64_e32 v[28:29], 0
	v_mov_b64_e32 v[34:35], 0
	v_mov_b64_e32 v[36:37], 0
	v_mov_b64_e32 v[42:43], 0
	v_mov_b64_e32 v[44:45], 0
	v_mov_b64_e32 v[46:47], 0
	v_mov_b64_e32 v[48:49], 0
	v_mov_b64_e32 v[58:59], 0
	v_mov_b64_e32 v[60:61], 0
	v_mov_b64_e32 v[62:63], 0
	v_mov_b64_e32 v[64:65], 0
	v_mov_b64_e32 v[66:67], 0
	v_mov_b64_e32 v[68:69], 0
	v_mov_b64_e32 v[70:71], 0
	v_mov_b64_e32 v[72:73], 0
	v_mov_b64_e32 v[82:83], 0
	v_mov_b64_e32 v[84:85], 0
	v_mov_b64_e32 v[86:87], 0
	v_mov_b64_e32 v[88:89], 0
	v_mov_b64_e32 v[94:95], 0
	v_mov_b64_e32 v[96:97], 0
	v_mov_b64_e32 v[102:103], 0
	v_mov_b64_e32 v[104:105], 0
	v_mov_b64_e32 v[114:115], 0
	v_mov_b64_e32 v[116:117], 0
	v_mov_b64_e32 v[118:119], 0
	v_mov_b64_e32 v[120:121], 0
	v_mov_b64_e32 v[74:75], 0
	v_mov_b64_e32 v[76:77], 0
	v_mov_b64_e32 v[78:79], 0
	v_mov_b64_e32 v[80:81], 0
	v_mov_b64_e32 v[90:91], 0
	v_mov_b64_e32 v[92:93], 0
	v_mov_b64_e32 v[98:99], 0
	v_mov_b64_e32 v[100:101], 0
	v_mov_b64_e32 v[106:107], 0
	v_mov_b64_e32 v[108:109], 0
	v_mov_b64_e32 v[110:111], 0
	v_mov_b64_e32 v[112:113], 0
	v_mov_b64_e32 v[122:123], 0
	v_mov_b64_e32 v[124:125], 0
	v_mov_b64_e32 v[126:127], 0
	v_mov_b64_e32 v[128:129], 0

;     __device__ bool next(int i, Unit& u) const { Unit b; if (!so.next(i / 3, b)) return false; const int br = i % 3; u.pm = br * 64 + b.pm; u.pn = br * 8 + b.pn; return true; }
; template <class Epi, class Sched>
; __device__ __forceinline__ void gemm_phase(const int tid, LAS unsigned char* lds, const Gemm g, const Sched& S, const Epi& E) {
;     ...
;     for (;;) {
;         const bool has_next = S.next(ui + 1, nxt);
;         const char* nA = has_next ? (const char*)g.A + (size_t)nxt.pm * tstepA : cA; const char* nB = has_next ? (const char*)g.Bt + (size_t)nxt.pn * tstepB : cB;
;         for (int t = 0; t < nt; t += 2) {
;     ...
;         for (int a = 0; a < 2; ++a)
; #pragma unroll
;             for (int b = 0; b < 2; ++b)
; #pragma unroll
;                 for (int m = 0; m < 4; ++m)
; #pragma unroll
;                     for (int n = 0; n < 2; ++n) acc[a][b][m][n] = (f32x4){0.f, 0.f, 0.f, 0.f};
;         cur = nxt; cA = nA; cB = nB; ++ui;
.LBB0_961:
	s_ashr_i32 s9, s8, 31
	s_lshl_b64 s[10:11], s[8:9], 20
	s_add_u32 s10, s27, s10
	s_addc_u32 s11, s28, s11
	s_and_b64 s[12:13], s[4:5], exec
	s_cselect_b32 s9, s11, s19
	s_cselect_b32 s58, s10, s18
	s_ashr_i32 s7, s6, 31
	s_lshl_b64 s[12:13], s[6:7], 20
	s_add_u32 s12, s29, s12
	s_addc_u32 s13, s30, s13
	s_and_b64 s[20:21], s[4:5], exec
	s_cselect_b32 s7, s13, s17
	s_cselect_b32 s59, s12, s16
	s_add_u32 s60, s16, 0x10000
	s_addc_u32 s61, s17, 0
	s_add_u32 s16, s18, 0xc000
	s_addc_u32 s17, s19, 0
	s_mov_b32 s62, -2
	v_mov_b64_e32 v[2:3], 0
	v_mov_b64_e32 v[4:5], 0
	v_mov_b64_e32 v[6:7], 0
	v_mov_b64_e32 v[8:9], 0
	v_mov_b64_e32 v[14:15], 0
	v_mov_b64_e32 v[16:17], 0
	v_mov_b64_e32 v[18:19], 0
	v_mov_b64_e32 v[20:21], 0
	v_mov_b64_e32 v[30:31], 0
	v_mov_b64_e32 v[32:33], 0
	v_mov_b64_e32 v[34:35], 0
	v_mov_b64_e32 v[36:37], 0
	v_mov_b64_e32 v[46:47], 0
	v_mov_b64_e32 v[48:49], 0
	v_mov_b64_e32 v[50:51], 0
	v_mov_b64_e32 v[52:53], 0
	v_mov_b64_e32 v[10:11], 0
	v_mov_b64_e32 v[12:13], 0
	v_mov_b64_e32 v[22:23], 0
	v_mov_b64_e32 v[24:25], 0
	v_mov_b64_e32 v[26:27], 0
	v_mov_b64_e32 v[28:29], 0
	v_mov_b64_e32 v[38:39], 0
	v_mov_b64_e32 v[40:41], 0
	v_mov_b64_e32 v[42:43], 0
	v_mov_b64_e32 v[44:45], 0
	v_mov_b64_e32 v[54:55], 0
	v_mov_b64_e32 v[56:57], 0
	v_mov_b64_e32 v[58:59], 0
	v_mov_b64_e32 v[60:61], 0
	v_mov_b64_e32 v[62:63], 0
	v_mov_b64_e32 v[64:65], 0
	v_mov_b64_e32 v[66:67], 0
	v_mov_b64_e32 v[68:69], 0
	v_mov_b64_e32 v[70:71], 0
	v_mov_b64_e32 v[72:73], 0
	v_mov_b64_e32 v[78:79], 0
	v_mov_b64_e32 v[80:81], 0
	v_mov_b64_e32 v[82:83], 0
	v_mov_b64_e32 v[84:85], 0
	v_mov_b64_e32 v[94:95], 0
	v_mov_b64_e32 v[96:97], 0
	v_mov_b64_e32 v[98:99], 0
	v_mov_b64_e32 v[100:101], 0
	v_mov_b64_e32 v[110:111], 0
	v_mov_b64_e32 v[112:113], 0
	v_mov_b64_e32 v[114:115], 0
	v_mov_b64_e32 v[116:117], 0
	v_mov_b64_e32 v[74:75], 0
	v_mov_b64_e32 v[76:77], 0
	v_mov_b64_e32 v[86:87], 0
	v_mov_b64_e32 v[88:89], 0
	v_mov_b64_e32 v[90:91], 0
	v_mov_b64_e32 v[92:93], 0
	v_mov_b64_e32 v[102:103], 0
	v_mov_b64_e32 v[104:105], 0
	v_mov_b64_e32 v[106:107], 0
	v_mov_b64_e32 v[108:109], 0
	v_mov_b64_e32 v[118:119], 0
	v_mov_b64_e32 v[120:121], 0
	v_mov_b64_e32 v[122:123], 0
	v_mov_b64_e32 v[124:125], 0
	v_mov_b64_e32 v[126:127], 0
	v_mov_b64_e32 v[128:129], 0

;     __device__ bool next(int i, Unit& u) const { Unit b; if (!so.next(i / 3, b)) return false; const int br = i % 3; u.pm = br * 64 + b.pm; u.pn = br * 8 + b.pn; return true; }
; template <class Epi, class Sched>
; __device__ __forceinline__ void gemm_phase(const int tid, LAS unsigned char* lds, const Gemm g, const Sched& S, const Epi& E) {
;     ...
;     for (;;) {
;         const bool has_next = S.next(ui + 1, nxt);
;         const char* nA = has_next ? (const char*)g.A + (size_t)nxt.pm * tstepA : cA; const char* nB = has_next ? (const char*)g.Bt + (size_t)nxt.pn * tstepB : cB;
;         for (int t = 0; t < nt; t += 2) {
;     ...
;         for (int a = 0; a < 2; ++a)
; #pragma unroll
;             for (int b = 0; b < 2; ++b)
; #pragma unroll
;                 for (int m = 0; m < 4; ++m)
; #pragma unroll
;                     for (int n = 0; n < 2; ++n) acc[a][b][m][n] = (f32x4){0.f, 0.f, 0.f, 0.f};
;         cur = nxt; cA = nA; cB = nB; ++ui;
.LBB0_1099:
	s_ashr_i32 s13, s12, 31
	s_lshl_b64 s[14:15], s[12:13], 20
	s_add_u32 s14, s30, s14
	s_addc_u32 s15, s31, s15
	s_and_b64 s[16:17], s[4:5], exec
	s_cselect_b32 s13, s15, s23
	s_cselect_b32 s64, s14, s22
	s_ashr_i32 s11, s10, 31
	s_lshl_b64 s[16:17], s[10:11], 20
	s_add_u32 s16, s34, s16
	s_addc_u32 s17, s35, s17
	s_and_b64 s[24:25], s[4:5], exec
	s_cselect_b32 s11, s17, s21
	s_cselect_b32 s65, s16, s20
	s_add_u32 s66, s20, 0x10000
	s_addc_u32 s67, s21, 0
	s_add_u32 s20, s22, 0xc000
	s_addc_u32 s21, s23, 0
	s_mov_b32 s76, -2
	v_mov_b64_e32 v[2:3], 0
	v_mov_b64_e32 v[4:5], 0
	v_mov_b64_e32 v[6:7], 0
	v_mov_b64_e32 v[8:9], 0
	v_mov_b64_e32 v[18:19], 0
	v_mov_b64_e32 v[20:21], 0
	v_mov_b64_e32 v[22:23], 0
	v_mov_b64_e32 v[24:25], 0
	v_mov_b64_e32 v[34:35], 0
	v_mov_b64_e32 v[36:37], 0
	v_mov_b64_e32 v[38:39], 0
	v_mov_b64_e32 v[40:41], 0
	v_mov_b64_e32 v[50:51], 0
	v_mov_b64_e32 v[52:53], 0
	v_mov_b64_e32 v[54:55], 0
	v_mov_b64_e32 v[56:57], 0
	v_mov_b64_e32 v[10:11], 0
	v_mov_b64_e32 v[12:13], 0
	v_mov_b64_e32 v[14:15], 0
	v_mov_b64_e32 v[16:17], 0
	v_mov_b64_e32 v[26:27], 0
	v_mov_b64_e32 v[28:29], 0
	v_mov_b64_e32 v[30:31], 0
	v_mov_b64_e32 v[32:33], 0
	v_mov_b64_e32 v[42:43], 0
	v_mov_b64_e32 v[44:45], 0
	v_mov_b64_e32 v[46:47], 0
	v_mov_b64_e32 v[48:49], 0
	v_mov_b64_e32 v[58:59], 0
	v_mov_b64_e32 v[60:61], 0
	v_mov_b64_e32 v[62:63], 0
	v_mov_b64_e32 v[64:65], 0
	v_mov_b64_e32 v[66:67], 0
	v_mov_b64_e32 v[68:69], 0
	v_mov_b64_e32 v[70:71], 0
	v_mov_b64_e32 v[72:73], 0
	v_mov_b64_e32 v[82:83], 0
	v_mov_b64_e32 v[84:85], 0
	v_mov_b64_e32 v[86:87], 0
	v_mov_b64_e32 v[88:89], 0
	v_mov_b64_e32 v[98:99], 0
	v_mov_b64_e32 v[100:101], 0
	v_mov_b64_e32 v[102:103], 0
	v_mov_b64_e32 v[104:105], 0
	v_mov_b64_e32 v[114:115], 0
	v_mov_b64_e32 v[116:117], 0
	v_mov_b64_e32 v[118:119], 0
	v_mov_b64_e32 v[120:121], 0
	v_mov_b64_e32 v[74:75], 0
	v_mov_b64_e32 v[76:77], 0
	v_mov_b64_e32 v[78:79], 0
	v_mov_b64_e32 v[80:81], 0
	v_mov_b64_e32 v[90:91], 0
	v_mov_b64_e32 v[92:93], 0
	v_mov_b64_e32 v[94:95], 0
	v_mov_b64_e32 v[96:97], 0
	v_mov_b64_e32 v[106:107], 0
	v_mov_b64_e32 v[108:109], 0
	v_mov_b64_e32 v[110:111], 0
	v_mov_b64_e32 v[112:113], 0
	v_mov_b64_e32 v[122:123], 0
	v_mov_b64_e32 v[124:125], 0
	v_mov_b64_e32 v[126:127], 0
	v_mov_b64_e32 v[128:129], 0

; template <class Epi, class Sched>
; __device__ __forceinline__ void gemm_phase(const int tid, LAS unsigned char* lds, const Gemm g, const Sched& S, const Epi& E) {
;     ...
;         for (int a = 0; a < 2; ++a)
; #pragma unroll
;             for (int b = 0; b < 2; ++b)
; #pragma unroll
;                 for (int m = 0; m < 4; ++m)
; #pragma unroll
;                     for (int n = 0; n < 2; ++n) acc[a][b][m][n] = (f32x4){0.f, 0.f, 0.f, 0.f};
;         cur = nxt; cA = nA; cB = nB; ++ui;
.LBB0_1170:
	s_add_u32 s60, s14, 0x10000
	s_addc_u32 s61, s15, 0
	s_add_u32 s14, s16, 0xc000
	s_addc_u32 s15, s17, 0
	s_mov_b32 s62, -2
	v_mov_b64_e32 v[2:3], 0
	v_mov_b64_e32 v[4:5], 0
	v_mov_b64_e32 v[6:7], 0
	v_mov_b64_e32 v[8:9], 0
	v_mov_b64_e32 v[14:15], 0
	v_mov_b64_e32 v[16:17], 0
	v_mov_b64_e32 v[18:19], 0
	v_mov_b64_e32 v[20:21], 0
	v_mov_b64_e32 v[30:31], 0
	v_mov_b64_e32 v[32:33], 0
	v_mov_b64_e32 v[34:35], 0
	v_mov_b64_e32 v[36:37], 0
	v_mov_b64_e32 v[46:47], 0
	v_mov_b64_e32 v[48:49], 0
	v_mov_b64_e32 v[50:51], 0
	v_mov_b64_e32 v[52:53], 0
	v_mov_b64_e32 v[10:11], 0
	v_mov_b64_e32 v[12:13], 0
	v_mov_b64_e32 v[22:23], 0
	v_mov_b64_e32 v[24:25], 0
	v_mov_b64_e32 v[26:27], 0
	v_mov_b64_e32 v[28:29], 0
	v_mov_b64_e32 v[38:39], 0
	v_mov_b64_e32 v[40:41], 0
	v_mov_b64_e32 v[42:43], 0
	v_mov_b64_e32 v[44:45], 0
	v_mov_b64_e32 v[54:55], 0
	v_mov_b64_e32 v[56:57], 0
	v_mov_b64_e32 v[58:59], 0
	v_mov_b64_e32 v[60:61], 0
	v_mov_b64_e32 v[62:63], 0
	v_mov_b64_e32 v[64:65], 0
	v_mov_b64_e32 v[66:67], 0
	v_mov_b64_e32 v[68:69], 0
	v_mov_b64_e32 v[70:71], 0
	v_mov_b64_e32 v[72:73], 0
	v_mov_b64_e32 v[78:79], 0
	v_mov_b64_e32 v[80:81], 0
	v_mov_b64_e32 v[82:83], 0
	v_mov_b64_e32 v[84:85], 0
	v_mov_b64_e32 v[94:95], 0
	v_mov_b64_e32 v[96:97], 0
	v_mov_b64_e32 v[98:99], 0
	v_mov_b64_e32 v[100:101], 0
	v_mov_b64_e32 v[110:111], 0
	v_mov_b64_e32 v[112:113], 0
	v_mov_b64_e32 v[114:115], 0
	v_mov_b64_e32 v[116:117], 0
	v_mov_b64_e32 v[74:75], 0
	v_mov_b64_e32 v[76:77], 0
	v_mov_b64_e32 v[86:87], 0
	v_mov_b64_e32 v[88:89], 0
	v_mov_b64_e32 v[90:91], 0
	v_mov_b64_e32 v[92:93], 0
	v_mov_b64_e32 v[102:103], 0
	v_mov_b64_e32 v[104:105], 0
	v_mov_b64_e32 v[106:107], 0
	v_mov_b64_e32 v[108:109], 0
	v_mov_b64_e32 v[118:119], 0
	v_mov_b64_e32 v[120:121], 0
	v_mov_b64_e32 v[122:123], 0
	v_mov_b64_e32 v[124:125], 0
	v_mov_b64_e32 v[126:127], 0
	v_mov_b64_e32 v[128:129], 0
